# v16 + attention P.V fragment reads as ds_read_b64 pairs off one base register (drops 4 address adds per half-tile)
# baseline (speedup 1.0000x reference)
; #define LAS __attribute__((address_space(3)))
; __device__ __forceinline__ unsigned cvtpk_s(float lo, float hi) { f32x2_t v = {lo, hi}; bf16x2_t b = __builtin_convertvector(v, bf16x2_t); return __builtin_bit_cast(unsigned, b); }
; template <int HF> ...
;     ...
;         float ls = 0.f;
; #pragma unroll
;         for (int r = 0; r < 16; ++r) { p[r] = __builtin_amdgcn_exp2f(p[r]); ls += p[r]; }
;         lsum[sub] += ls;
;         pw[sub][0] = (u32x4){cvtpk_s(p[0], p[1]), cvtpk_s(p[2], p[3]), cvtpk_s(p[4], p[5]), cvtpk_s(p[6], p[7])};
;         pw[sub][1] = (u32x4){cvtpk_s(p[8], p[9]), cvtpk_s(p[10], p[11]), cvtpk_s(p[12], p[13]), cvtpk_s(p[14], p[15])};
;         __builtin_amdgcn_sched_barrier(0);
;         if (sub == 0 && stage) {
;             if (HF == 0) { *(LAS u32x4*)sdst = st0; *(LAS u32x4*)(sdst + 32 * KROW) = st1; }
;             else { *(LAS u32x2*)sdst = (u32x2){st0.x, st0.y}; *(LAS u32x2*)(sdst + 8) = (u32x2){st0.z, st0.w}; *(LAS u32x2*)(sdst + 64 * VROW) = (u32x2){st1.x, st1.y}; *(LAS u32x2*)(sdst + 64 * VROW + 8) = (u32x2){st1.z, st1.w}; }
;             __builtin_amdgcn_sched_barrier(0);
;         }
;     }
;     ...
;     bf16x8 vcur = AT_VFRAG(0);
;     __builtin_amdgcn_s_setprio(1);
; #pragma unroll
;     for (int idx = 0; idx < 8; ++idx) {
;         bf16x8 vnext = vcur;
;         if (idx + 1 < 8) vnext = AT_VFRAG(idx + 1);
;         const int kk = idx >> 2, d = idx & 3;
;         o[0][d] = __builtin_amdgcn_mfma_f32_32x32x16_bf16(vcur, __builtin_bit_cast(bf16x8, pw[0][kk]), o[0][d], 0, 0, 0);
;         o[1][d] = __builtin_amdgcn_mfma_f32_32x32x16_bf16(vcur, __builtin_bit_cast(bf16x8, pw[1][kk]), o[1][d], 0, 0, 0);
;         __builtin_amdgcn_sched_barrier(0);
;         vcur = vnext;
;     }
;     __builtin_amdgcn_s_setprio(0);
.LBB0_258:
	v_exp_f32_e32 v227, v144
	v_exp_f32_e32 v248, v145
	v_exp_f32_e32 v249, v146
	v_exp_f32_e32 v250, v147
	v_exp_f32_e32 v148, v148
	v_add_f32_e32 v144, v248, v227
	v_exp_f32_e32 v149, v149
	v_add_f32_e32 v144, v249, v144
	v_exp_f32_e32 v150, v150
	v_add_f32_e32 v144, v250, v144
	v_exp_f32_e32 v151, v151
	v_add_f32_e32 v144, v148, v144
	v_exp_f32_e32 v152, v152
	v_add_f32_e32 v144, v149, v144
	v_exp_f32_e32 v153, v153
	v_add_f32_e32 v144, v150, v144
	v_exp_f32_e32 v145, v154
	v_add_f32_e32 v144, v151, v144
	v_exp_f32_e32 v154, v155
	v_add_f32_e32 v144, v152, v144
	v_exp_f32_e32 v146, v156
	v_add_f32_e32 v144, v153, v144
	v_exp_f32_e32 v155, v157
	v_add_f32_e32 v144, v145, v144
	v_exp_f32_e32 v147, v158
	v_add_f32_e32 v144, v154, v144
	v_exp_f32_e32 v156, v159
	v_add_f32_e32 v144, v146, v144
	v_exp_f32_e32 v128, v128
	v_add_f32_e32 v144, v155, v144
	v_exp_f32_e32 v129, v129
	v_add_f32_e32 v144, v147, v144
	v_exp_f32_e32 v130, v130
	v_add_f32_e32 v144, v156, v144
	v_exp_f32_e32 v131, v131
	v_add_f32_e32 v224, v224, v144
	v_cvt_pk_bf16_f32 v144, v152, v153
	v_exp_f32_e32 v132, v132
	v_add_f32_e32 v152, v129, v128
	v_exp_f32_e32 v133, v133
	v_add_f32_e32 v152, v130, v152
	v_exp_f32_e32 v134, v134
	v_add_f32_e32 v152, v131, v152
	v_exp_f32_e32 v135, v135
	v_add_f32_e32 v152, v132, v152
	v_exp_f32_e32 v136, v136
	v_add_f32_e32 v152, v133, v152
	v_exp_f32_e32 v137, v137
	v_add_f32_e32 v152, v134, v152
	v_exp_f32_e32 v138, v138
	v_add_f32_e32 v152, v135, v152
	v_exp_f32_e32 v139, v139
	v_add_f32_e32 v152, v136, v152
	v_exp_f32_e32 v140, v140
	v_add_f32_e32 v152, v137, v152
	v_exp_f32_e32 v141, v141
	v_add_f32_e32 v152, v138, v152
	v_exp_f32_e32 v142, v142
	v_add_f32_e32 v152, v139, v152
	v_exp_f32_e32 v143, v143
	v_add_f32_e32 v152, v140, v152
	v_add_f32_e32 v152, v141, v152
	v_add_f32_e32 v152, v142, v152
	v_add_f32_e32 v152, v143, v152
	v_add_f32_e32 v225, v225, v152
	v_cvt_pk_bf16_f32 v147, v147, v156
	v_cvt_pk_bf16_f32 v146, v146, v155
	v_cvt_pk_bf16_f32 v145, v145, v154
	v_cvt_pk_bf16_f32 v151, v150, v151
	v_cvt_pk_bf16_f32 v150, v148, v149
	v_cvt_pk_bf16_f32 v149, v249, v250
	v_cvt_pk_bf16_f32 v148, v227, v248
	v_cvt_pk_bf16_f32 v128, v128, v129
	v_cvt_pk_bf16_f32 v129, v130, v131
	v_cvt_pk_bf16_f32 v130, v132, v133
	v_cvt_pk_bf16_f32 v131, v134, v135
	v_cvt_pk_bf16_f32 v132, v136, v137
	v_cvt_pk_bf16_f32 v133, v138, v139
	v_cvt_pk_bf16_f32 v134, v140, v141
	v_cvt_pk_bf16_f32 v135, v142, v143
	v_add_u32_e32 v152, s91, v236
	ds_read_b64 v[136:137], v152 offset:34816
	ds_read_b64 v[138:139], v152 offset:34832
	ds_read_b64 v[140:141], v152 offset:39168
	ds_read_b64 v[142:143], v152 offset:39184
	ds_read_b64 v[248:249], v152 offset:43520
	ds_read_b64 v[250:251], v152 offset:43536
	s_setprio 1
	s_waitcnt lgkmcnt(4)
	v_mfma_f32_32x32x16_bf16 v[64:79], v[136:139], v[148:151], v[64:79]
	ds_read_b64 v[252:253], v152 offset:47872
	ds_read_b64 v[254:255], v152 offset:47888
	v_mfma_f32_32x32x16_bf16 v[112:127], v[136:139], v[128:131], v[112:127]
	s_waitcnt lgkmcnt(4)
	v_mfma_f32_32x32x16_bf16 v[48:63], v[140:143], v[148:151], v[48:63]
	ds_read_b64 v[136:137], v152 offset:34848
	ds_read_b64 v[138:139], v152 offset:34864
	v_mfma_f32_32x32x16_bf16 v[96:111], v[140:143], v[128:131], v[96:111]
	s_waitcnt lgkmcnt(4)
	v_mfma_f32_32x32x16_bf16 v[16:31], v[248:251], v[148:151], v[16:31]
	ds_read_b64 v[140:141], v152 offset:39200
	ds_read_b64 v[142:143], v152 offset:39216
	v_mfma_f32_32x32x16_bf16 v[80:95], v[248:251], v[128:131], v[80:95]
	s_waitcnt lgkmcnt(4)
	v_mfma_f32_32x32x16_bf16 v[0:15], v[252:255], v[148:151], v[0:15]
	ds_read_b64 v[248:249], v152 offset:43552
	ds_read_b64 v[250:251], v152 offset:43568
	v_mfma_f32_32x32x16_bf16 v[32:47], v[252:255], v[128:131], v[32:47]
	s_waitcnt lgkmcnt(4)
	v_mfma_f32_32x32x16_bf16 v[64:79], v[136:139], v[144:147], v[64:79]
	ds_read_b64 v[252:253], v152 offset:47904
	ds_read_b64 v[254:255], v152 offset:47920
	v_mfma_f32_32x32x16_bf16 v[112:127], v[136:139], v[132:135], v[112:127]
	s_waitcnt lgkmcnt(4)
	v_mfma_f32_32x32x16_bf16 v[48:63], v[140:143], v[144:147], v[48:63]
	v_mfma_f32_32x32x16_bf16 v[96:111], v[140:143], v[132:135], v[96:111]
	s_waitcnt lgkmcnt(2)
	v_mfma_f32_32x32x16_bf16 v[16:31], v[248:251], v[144:147], v[16:31]
	v_mfma_f32_32x32x16_bf16 v[80:95], v[248:251], v[132:135], v[80:95]
	s_waitcnt lgkmcnt(0)
	v_mfma_f32_32x32x16_bf16 v[0:15], v[252:255], v[144:147], v[0:15]
	v_mfma_f32_32x32x16_bf16 v[32:47], v[252:255], v[132:135], v[32:47]
	s_setprio 0

; #define LAS __attribute__((address_space(3)))
; __device__ __forceinline__ unsigned cvtpk_s(float lo, float hi) { f32x2_t v = {lo, hi}; bf16x2_t b = __builtin_convertvector(v, bf16x2_t); return __builtin_bit_cast(unsigned, b); }
; template <int HF> ...
;     ...
;         float ls = 0.f;
; #pragma unroll
;         for (int r = 0; r < 16; ++r) { p[r] = __builtin_amdgcn_exp2f(p[r]); ls += p[r]; }
;         lsum[sub] += ls;
;         pw[sub][0] = (u32x4){cvtpk_s(p[0], p[1]), cvtpk_s(p[2], p[3]), cvtpk_s(p[4], p[5]), cvtpk_s(p[6], p[7])};
;         pw[sub][1] = (u32x4){cvtpk_s(p[8], p[9]), cvtpk_s(p[10], p[11]), cvtpk_s(p[12], p[13]), cvtpk_s(p[14], p[15])};
;         __builtin_amdgcn_sched_barrier(0);
;         if (sub == 0 && stage) {
;             if (HF == 0) { *(LAS u32x4*)sdst = st0; *(LAS u32x4*)(sdst + 32 * KROW) = st1; }
;             else { *(LAS u32x2*)sdst = (u32x2){st0.x, st0.y}; *(LAS u32x2*)(sdst + 8) = (u32x2){st0.z, st0.w}; *(LAS u32x2*)(sdst + 64 * VROW) = (u32x2){st1.x, st1.y}; *(LAS u32x2*)(sdst + 64 * VROW + 8) = (u32x2){st1.z, st1.w}; }
;             __builtin_amdgcn_sched_barrier(0);
;         }
;     }
;     ...
;     bf16x8 vcur = AT_VFRAG(0);
;     __builtin_amdgcn_s_setprio(1);
; #pragma unroll
;     for (int idx = 0; idx < 8; ++idx) {
;         bf16x8 vnext = vcur;
;         if (idx + 1 < 8) vnext = AT_VFRAG(idx + 1);
;         const int kk = idx >> 2, d = idx & 3;
;         o[0][d] = __builtin_amdgcn_mfma_f32_32x32x16_bf16(vcur, __builtin_bit_cast(bf16x8, pw[0][kk]), o[0][d], 0, 0, 0);
;         o[1][d] = __builtin_amdgcn_mfma_f32_32x32x16_bf16(vcur, __builtin_bit_cast(bf16x8, pw[1][kk]), o[1][d], 0, 0, 0);
;         __builtin_amdgcn_sched_barrier(0);
;         vcur = vnext;
;     }
;     __builtin_amdgcn_s_setprio(0);
.LBB0_272:
	v_exp_f32_e32 v227, v144
	v_exp_f32_e32 v247, v145
	v_exp_f32_e32 v248, v146
	v_exp_f32_e32 v249, v147
	v_exp_f32_e32 v148, v148
	v_add_f32_e32 v144, v247, v227
	v_exp_f32_e32 v149, v149
	v_add_f32_e32 v144, v248, v144
	v_exp_f32_e32 v150, v150
	v_add_f32_e32 v144, v249, v144
	v_exp_f32_e32 v151, v151
	v_add_f32_e32 v144, v148, v144
	v_exp_f32_e32 v152, v152
	v_add_f32_e32 v144, v149, v144
	v_exp_f32_e32 v153, v153
	v_add_f32_e32 v144, v150, v144
	v_exp_f32_e32 v145, v154
	v_add_f32_e32 v144, v151, v144
	v_exp_f32_e32 v154, v155
	v_add_f32_e32 v144, v152, v144
	v_exp_f32_e32 v146, v156
	v_add_f32_e32 v144, v153, v144
	v_exp_f32_e32 v155, v157
	v_add_f32_e32 v144, v145, v144
	v_exp_f32_e32 v147, v158
	v_add_f32_e32 v144, v154, v144
	v_exp_f32_e32 v156, v159
	v_add_f32_e32 v144, v146, v144
	v_exp_f32_e32 v128, v128
	v_add_f32_e32 v144, v155, v144
	v_exp_f32_e32 v129, v129
	v_add_f32_e32 v144, v147, v144
	v_exp_f32_e32 v130, v130
	v_add_f32_e32 v144, v156, v144
	v_exp_f32_e32 v131, v131
	v_add_f32_e32 v224, v224, v144
	v_cvt_pk_bf16_f32 v144, v152, v153
	v_exp_f32_e32 v132, v132
	v_add_f32_e32 v152, v129, v128
	v_exp_f32_e32 v133, v133
	v_add_f32_e32 v152, v130, v152
	v_exp_f32_e32 v134, v134
	v_add_f32_e32 v152, v131, v152
	v_exp_f32_e32 v135, v135
	v_add_f32_e32 v152, v132, v152
	v_exp_f32_e32 v136, v136
	v_add_f32_e32 v152, v133, v152
	v_exp_f32_e32 v137, v137
	v_add_f32_e32 v152, v134, v152
	v_exp_f32_e32 v138, v138
	v_add_f32_e32 v152, v135, v152
	v_exp_f32_e32 v139, v139
	v_add_f32_e32 v152, v136, v152
	v_exp_f32_e32 v140, v140
	v_add_f32_e32 v152, v137, v152
	v_exp_f32_e32 v141, v141
	v_add_f32_e32 v152, v138, v152
	v_exp_f32_e32 v142, v142
	v_add_f32_e32 v152, v139, v152
	v_exp_f32_e32 v143, v143
	v_add_f32_e32 v152, v140, v152
	v_add_f32_e32 v152, v141, v152
	v_add_f32_e32 v152, v142, v152
	v_add_f32_e32 v152, v143, v152
	v_add_f32_e32 v225, v225, v152
	v_cvt_pk_bf16_f32 v147, v147, v156
	v_cvt_pk_bf16_f32 v146, v146, v155
	v_cvt_pk_bf16_f32 v145, v145, v154
	v_cvt_pk_bf16_f32 v151, v150, v151
	v_cvt_pk_bf16_f32 v150, v148, v149
	v_cvt_pk_bf16_f32 v149, v248, v249
	v_cvt_pk_bf16_f32 v148, v227, v247
	v_cvt_pk_bf16_f32 v128, v128, v129
	v_cvt_pk_bf16_f32 v129, v130, v131
	v_cvt_pk_bf16_f32 v130, v132, v133
	v_cvt_pk_bf16_f32 v131, v134, v135
	v_cvt_pk_bf16_f32 v132, v136, v137
	v_cvt_pk_bf16_f32 v133, v138, v139
	v_cvt_pk_bf16_f32 v134, v140, v141
	v_cvt_pk_bf16_f32 v135, v142, v143
	v_add_u32_e32 v152, s91, v236
	ds_read_b64 v[136:137], v152 offset:34880
	ds_read_b64 v[138:139], v152 offset:34896
	ds_read_b64 v[140:141], v152 offset:39232
	ds_read_b64 v[142:143], v152 offset:39248
	ds_read_b64 v[248:249], v152 offset:43584
	ds_read_b64 v[250:251], v152 offset:43600
	s_setprio 1
	s_waitcnt lgkmcnt(4)
	v_mfma_f32_32x32x16_bf16 v[64:79], v[136:139], v[148:151], v[64:79]
	ds_read_b64 v[252:253], v152 offset:47936
	ds_read_b64 v[254:255], v152 offset:47952
	v_mfma_f32_32x32x16_bf16 v[112:127], v[136:139], v[128:131], v[112:127]
	s_waitcnt lgkmcnt(4)
	v_mfma_f32_32x32x16_bf16 v[48:63], v[140:143], v[148:151], v[48:63]
	ds_read_b64 v[136:137], v152 offset:34912
	ds_read_b64 v[138:139], v152 offset:34928
	v_mfma_f32_32x32x16_bf16 v[96:111], v[140:143], v[128:131], v[96:111]
	s_waitcnt lgkmcnt(4)
	v_mfma_f32_32x32x16_bf16 v[16:31], v[248:251], v[148:151], v[16:31]
	ds_read_b64 v[140:141], v152 offset:39264
	ds_read_b64 v[142:143], v152 offset:39280
	v_mfma_f32_32x32x16_bf16 v[80:95], v[248:251], v[128:131], v[80:95]
	s_waitcnt lgkmcnt(4)
	v_mfma_f32_32x32x16_bf16 v[0:15], v[252:255], v[148:151], v[0:15]
	ds_read_b64 v[248:249], v152 offset:43616
	ds_read_b64 v[250:251], v152 offset:43632
	v_mfma_f32_32x32x16_bf16 v[32:47], v[252:255], v[128:131], v[32:47]
	s_waitcnt lgkmcnt(4)
	v_mfma_f32_32x32x16_bf16 v[64:79], v[136:139], v[144:147], v[64:79]
	ds_read_b64 v[252:253], v152 offset:47968
	ds_read_b64 v[254:255], v152 offset:47984
	v_mfma_f32_32x32x16_bf16 v[112:127], v[136:139], v[132:135], v[112:127]
	s_waitcnt lgkmcnt(4)
	v_mfma_f32_32x32x16_bf16 v[48:63], v[140:143], v[144:147], v[48:63]
	v_mfma_f32_32x32x16_bf16 v[96:111], v[140:143], v[132:135], v[96:111]
	s_waitcnt lgkmcnt(2)
	v_mfma_f32_32x32x16_bf16 v[16:31], v[248:251], v[144:147], v[16:31]
	v_mfma_f32_32x32x16_bf16 v[80:95], v[248:251], v[132:135], v[80:95]
	s_waitcnt lgkmcnt(0)
	v_mfma_f32_32x32x16_bf16 v[0:15], v[252:255], v[144:147], v[0:15]
	v_mfma_f32_32x32x16_bf16 v[32:47], v[252:255], v[132:135], v[32:47]
	s_setprio 0
